# layer-0 weight conversion moved to the 224 workgroups idle during the adaLN phase (static split), on top of the 256x128 GEMM tiles
# speedup vs baseline: 1.0680x; 1.0009x over previous
; __device__ __forceinline__ void phase_cvt(const Params& p, int l, char* smem) {
;   const int total = p.job_tiles[l];
;   for (int t = blockIdx.x; t < total; t += gridDim.x) {
;     int ji = 0;
; #pragma unroll 1
;     for (int q = 1; q < 15; ++q) if (t >= p.jobs[l * 15 + q].tile0) ji = q;
;     const CvtJob& j = p.jobs[l * 15 + ji];
;     cvt_tile(j, t - j.tile0, smem);
;   }
; }
.LBB0_32:
	s_cmp_gt_u32 s91, 13
	s_cselect_b64 s[28:29], -1, 0
	s_and_b64 s[22:23], s[28:29], exec
	s_cselect_b32 s77, -14, 0
	s_add_i32 s77, s77, s91
	s_cmp_lg_u32 s77, 0
	s_cselect_b64 s[22:23], -1, 0
	v_writelane_b32 v250, s22, 31
	s_and_b64 vcc, exec, s[22:23]
	s_nop 0
	v_writelane_b32 v250, s23, 32
	s_cbranch_vccnz .LBB0_62
	v_cndmask_b32_e64 v0, 0, 1, s[28:29]
	s_nop 0
	v_readfirstlane_b32 s22, v0
	s_lshl_b32 s22, s22, 2
	s_load_dword s22, s[0:1], s22 offset:0x6a8
	s_waitcnt lgkmcnt(0)
	s_mov_b32 s100, s3
	s_mov_b32 s101, s2
	s_cmp_gt_u32 s91, 13
	s_cbranch_scc1 .Lcvt_all
	s_cmpk_lt_u32 s3, 0x180
	s_cbranch_scc1 .Lcvt_all
	s_sub_i32 s101, s2, 0x120
	s_sub_i32 s100, s3, 0x120
	s_cmp_lt_i32 s101, 0
	s_cbranch_scc1 .LBB0_50
.Lcvt_all:
	s_cmp_ge_i32 s101, s22
	s_cbranch_scc1 .LBB0_50
	s_and_b64 s[34:35], s[28:29], exec
	s_cselect_b32 s23, 15, 0
	s_mov_b32 s44, s23
	s_mov_b32 s45, s101
	s_branch .LBB0_36
.LBB0_35:
	s_or_b64 exec, exec, s[40:41]
	s_add_i32 s45, s45, s100
	s_cmp_lt_i32 s45, s22
	s_barrier
	s_cbranch_scc0 .LBB0_50
